# SwiGLU (phase J) epilogue rewritten: 4 independent pairs interleaved stage by stage with packed f32 mul/add instead of one serial chain per element
# speedup vs baseline: 1.0039x; 1.0039x over previous
.LBB0_1403:
	v_lshl_add_u32 v142, s64, 8, v138
	v_lshl_or_b32 v144, s61, 7, v140
	v_ashrrev_i32_e32 v145, 31, v144
	s_andn2_b64 vcc, exec, s[38:39]
	v_mov_b64_e32 v[146:147], s[40:41]
	v_mad_i64_i32 v[146:147], s[28:29], v142, s3, v[146:147]
	v_lshlrev_b64 v[148:149], 1, v[144:145]
	v_lshl_add_u64 v[146:147], v[146:147], 0, v[148:149]
	v_mov_b32_e32 v150, 0xbfb8aa3b
	v_mov_b32_e32 v151, v150
	s_mov_b64 s[28:29], 0x2c000
	v_pk_mul_f32 v[152:153], v[124:125], v[150:151]
	v_pk_mul_f32 v[154:155], v[126:127], v[150:151]
	v_pk_mul_f32 v[156:157], v[116:117], v[150:151]
	v_pk_mul_f32 v[158:159], v[118:119], v[150:151]
	v_exp_f32_e32 v152, v152
	v_exp_f32_e32 v153, v153
	v_exp_f32_e32 v154, v154
	v_exp_f32_e32 v155, v155
	v_exp_f32_e32 v156, v156
	v_exp_f32_e32 v157, v157
	v_exp_f32_e32 v158, v158
	v_exp_f32_e32 v159, v159
	v_pk_add_f32 v[152:153], v[152:153], 1.0 op_sel_hi:[1,0]
	v_pk_add_f32 v[154:155], v[154:155], 1.0 op_sel_hi:[1,0]
	v_pk_add_f32 v[156:157], v[156:157], 1.0 op_sel_hi:[1,0]
	v_pk_add_f32 v[158:159], v[158:159], 1.0 op_sel_hi:[1,0]
	v_rcp_f32_e32 v152, v152
	v_rcp_f32_e32 v153, v153
	v_rcp_f32_e32 v154, v154
	v_rcp_f32_e32 v155, v155
	v_rcp_f32_e32 v156, v156
	v_rcp_f32_e32 v157, v157
	v_rcp_f32_e32 v158, v158
	v_rcp_f32_e32 v159, v159
	v_pk_mul_f32 v[152:153], v[124:125], v[152:153]
	v_pk_mul_f32 v[154:155], v[126:127], v[154:155]
	v_pk_mul_f32 v[156:157], v[116:117], v[156:157]
	v_pk_mul_f32 v[158:159], v[118:119], v[158:159]
	v_pk_mul_f32 v[120:121], v[152:153], v[120:121]
	v_pk_mul_f32 v[122:123], v[154:155], v[122:123]
	v_pk_mul_f32 v[112:113], v[156:157], v[112:113]
	v_pk_mul_f32 v[114:115], v[158:159], v[114:115]
	v_cvt_pk_bf16_f32 v160, v120, v121
	v_cvt_pk_bf16_f32 v161, v122, v123
	v_cvt_pk_bf16_f32 v162, v112, v113
	v_cvt_pk_bf16_f32 v163, v114, v115
	global_store_dwordx4 v[146:147], v[160:163], off
	v_lshl_add_u64 v[146:147], v[146:147], 0, s[28:29]
	v_pk_mul_f32 v[152:153], v[108:109], v[150:151]
	v_pk_mul_f32 v[154:155], v[110:111], v[150:151]
	v_pk_mul_f32 v[156:157], v[100:101], v[150:151]
	v_pk_mul_f32 v[158:159], v[102:103], v[150:151]
	v_exp_f32_e32 v152, v152
	v_exp_f32_e32 v153, v153
	v_exp_f32_e32 v154, v154
	v_exp_f32_e32 v155, v155
	v_exp_f32_e32 v156, v156
	v_exp_f32_e32 v157, v157
	v_exp_f32_e32 v158, v158
	v_exp_f32_e32 v159, v159
	v_pk_add_f32 v[152:153], v[152:153], 1.0 op_sel_hi:[1,0]
	v_pk_add_f32 v[154:155], v[154:155], 1.0 op_sel_hi:[1,0]
	v_pk_add_f32 v[156:157], v[156:157], 1.0 op_sel_hi:[1,0]
	v_pk_add_f32 v[158:159], v[158:159], 1.0 op_sel_hi:[1,0]
	v_rcp_f32_e32 v152, v152
	v_rcp_f32_e32 v153, v153
	v_rcp_f32_e32 v154, v154
	v_rcp_f32_e32 v155, v155
	v_rcp_f32_e32 v156, v156
	v_rcp_f32_e32 v157, v157
	v_rcp_f32_e32 v158, v158
	v_rcp_f32_e32 v159, v159
	v_pk_mul_f32 v[152:153], v[108:109], v[152:153]
	v_pk_mul_f32 v[154:155], v[110:111], v[154:155]
	v_pk_mul_f32 v[156:157], v[100:101], v[156:157]
	v_pk_mul_f32 v[158:159], v[102:103], v[158:159]
	v_pk_mul_f32 v[104:105], v[152:153], v[104:105]
	v_pk_mul_f32 v[106:107], v[154:155], v[106:107]
	v_pk_mul_f32 v[96:97], v[156:157], v[96:97]
	v_pk_mul_f32 v[98:99], v[158:159], v[98:99]
	v_cvt_pk_bf16_f32 v164, v104, v105
	v_cvt_pk_bf16_f32 v165, v106, v107
	v_cvt_pk_bf16_f32 v166, v96, v97
	v_cvt_pk_bf16_f32 v167, v98, v99
	global_store_dwordx4 v[146:147], v[164:167], off
	v_lshl_add_u64 v[146:147], v[146:147], 0, s[28:29]
	v_pk_mul_f32 v[152:153], v[92:93], v[150:151]
	v_pk_mul_f32 v[154:155], v[94:95], v[150:151]
	v_pk_mul_f32 v[156:157], v[84:85], v[150:151]
	v_pk_mul_f32 v[158:159], v[86:87], v[150:151]
	v_exp_f32_e32 v152, v152
	v_exp_f32_e32 v153, v153
	v_exp_f32_e32 v154, v154
	v_exp_f32_e32 v155, v155
	v_exp_f32_e32 v156, v156
	v_exp_f32_e32 v157, v157
	v_exp_f32_e32 v158, v158
	v_exp_f32_e32 v159, v159
	v_pk_add_f32 v[152:153], v[152:153], 1.0 op_sel_hi:[1,0]
	v_pk_add_f32 v[154:155], v[154:155], 1.0 op_sel_hi:[1,0]
	v_pk_add_f32 v[156:157], v[156:157], 1.0 op_sel_hi:[1,0]
	v_pk_add_f32 v[158:159], v[158:159], 1.0 op_sel_hi:[1,0]
	v_rcp_f32_e32 v152, v152
	v_rcp_f32_e32 v153, v153
	v_rcp_f32_e32 v154, v154
	v_rcp_f32_e32 v155, v155
	v_rcp_f32_e32 v156, v156
	v_rcp_f32_e32 v157, v157
	v_rcp_f32_e32 v158, v158
	v_rcp_f32_e32 v159, v159
	v_pk_mul_f32 v[152:153], v[92:93], v[152:153]
	v_pk_mul_f32 v[154:155], v[94:95], v[154:155]
	v_pk_mul_f32 v[156:157], v[84:85], v[156:157]
	v_pk_mul_f32 v[158:159], v[86:87], v[158:159]
	v_pk_mul_f32 v[88:89], v[152:153], v[88:89]
	v_pk_mul_f32 v[90:91], v[154:155], v[90:91]
	v_pk_mul_f32 v[80:81], v[156:157], v[80:81]
	v_pk_mul_f32 v[82:83], v[158:159], v[82:83]
	v_cvt_pk_bf16_f32 v160, v88, v89
	v_cvt_pk_bf16_f32 v161, v90, v91
	v_cvt_pk_bf16_f32 v162, v80, v81
	v_cvt_pk_bf16_f32 v163, v82, v83
	global_store_dwordx4 v[146:147], v[160:163], off
	v_lshl_add_u64 v[146:147], v[146:147], 0, s[28:29]
	v_pk_mul_f32 v[152:153], v[76:77], v[150:151]
	v_pk_mul_f32 v[154:155], v[78:79], v[150:151]
	v_pk_mul_f32 v[156:157], v[68:69], v[150:151]
	v_pk_mul_f32 v[158:159], v[70:71], v[150:151]
	v_exp_f32_e32 v152, v152
	v_exp_f32_e32 v153, v153
	v_exp_f32_e32 v154, v154
	v_exp_f32_e32 v155, v155
	v_exp_f32_e32 v156, v156
	v_exp_f32_e32 v157, v157
	v_exp_f32_e32 v158, v158
	v_exp_f32_e32 v159, v159
	v_pk_add_f32 v[152:153], v[152:153], 1.0 op_sel_hi:[1,0]
	v_pk_add_f32 v[154:155], v[154:155], 1.0 op_sel_hi:[1,0]
	v_pk_add_f32 v[156:157], v[156:157], 1.0 op_sel_hi:[1,0]
	v_pk_add_f32 v[158:159], v[158:159], 1.0 op_sel_hi:[1,0]
	v_rcp_f32_e32 v152, v152
	v_rcp_f32_e32 v153, v153
	v_rcp_f32_e32 v154, v154
	v_rcp_f32_e32 v155, v155
	v_rcp_f32_e32 v156, v156
	v_rcp_f32_e32 v157, v157
	v_rcp_f32_e32 v158, v158
	v_rcp_f32_e32 v159, v159
	v_pk_mul_f32 v[152:153], v[76:77], v[152:153]
	v_pk_mul_f32 v[154:155], v[78:79], v[154:155]
	v_pk_mul_f32 v[156:157], v[68:69], v[156:157]
	v_pk_mul_f32 v[158:159], v[70:71], v[158:159]
	v_pk_mul_f32 v[72:73], v[152:153], v[72:73]
	v_pk_mul_f32 v[74:75], v[154:155], v[74:75]
	v_pk_mul_f32 v[64:65], v[156:157], v[64:65]
	v_pk_mul_f32 v[66:67], v[158:159], v[66:67]
	v_cvt_pk_bf16_f32 v164, v72, v73
	v_cvt_pk_bf16_f32 v165, v74, v75
	v_cvt_pk_bf16_f32 v166, v64, v65
	v_cvt_pk_bf16_f32 v167, v66, v67
	global_store_dwordx4 v[146:147], v[164:167], off
	s_mov_b64 s[28:29], 0xdc000
	v_lshl_add_u64 v[146:147], v[146:147], 0, s[28:29]
	s_mov_b64 s[28:29], 0x2c000
	v_pk_mul_f32 v[152:153], v[60:61], v[150:151]
	v_pk_mul_f32 v[154:155], v[62:63], v[150:151]
	v_pk_mul_f32 v[156:157], v[52:53], v[150:151]
	v_pk_mul_f32 v[158:159], v[54:55], v[150:151]
	v_exp_f32_e32 v152, v152
	v_exp_f32_e32 v153, v153
	v_exp_f32_e32 v154, v154
	v_exp_f32_e32 v155, v155
	v_exp_f32_e32 v156, v156
	v_exp_f32_e32 v157, v157
	v_exp_f32_e32 v158, v158
	v_exp_f32_e32 v159, v159
	v_pk_add_f32 v[152:153], v[152:153], 1.0 op_sel_hi:[1,0]
	v_pk_add_f32 v[154:155], v[154:155], 1.0 op_sel_hi:[1,0]
	v_pk_add_f32 v[156:157], v[156:157], 1.0 op_sel_hi:[1,0]
	v_pk_add_f32 v[158:159], v[158:159], 1.0 op_sel_hi:[1,0]
	v_rcp_f32_e32 v152, v152
	v_rcp_f32_e32 v153, v153
	v_rcp_f32_e32 v154, v154
	v_rcp_f32_e32 v155, v155
	v_rcp_f32_e32 v156, v156
	v_rcp_f32_e32 v157, v157
	v_rcp_f32_e32 v158, v158
	v_rcp_f32_e32 v159, v159
	v_pk_mul_f32 v[152:153], v[60:61], v[152:153]
	v_pk_mul_f32 v[154:155], v[62:63], v[154:155]
	v_pk_mul_f32 v[156:157], v[52:53], v[156:157]
	v_pk_mul_f32 v[158:159], v[54:55], v[158:159]
	v_pk_mul_f32 v[56:57], v[152:153], v[56:57]
	v_pk_mul_f32 v[58:59], v[154:155], v[58:59]
	v_pk_mul_f32 v[48:49], v[156:157], v[48:49]
	v_pk_mul_f32 v[50:51], v[158:159], v[50:51]
	v_cvt_pk_bf16_f32 v160, v56, v57
	v_cvt_pk_bf16_f32 v161, v58, v59
	v_cvt_pk_bf16_f32 v162, v48, v49
	v_cvt_pk_bf16_f32 v163, v50, v51
	global_store_dwordx4 v[146:147], v[160:163], off
	v_lshl_add_u64 v[146:147], v[146:147], 0, s[28:29]
	v_pk_mul_f32 v[152:153], v[44:45], v[150:151]
	v_pk_mul_f32 v[154:155], v[46:47], v[150:151]
	v_pk_mul_f32 v[156:157], v[36:37], v[150:151]
	v_pk_mul_f32 v[158:159], v[38:39], v[150:151]
	v_exp_f32_e32 v152, v152
	v_exp_f32_e32 v153, v153
	v_exp_f32_e32 v154, v154
	v_exp_f32_e32 v155, v155
	v_exp_f32_e32 v156, v156
	v_exp_f32_e32 v157, v157
	v_exp_f32_e32 v158, v158
	v_exp_f32_e32 v159, v159
	v_pk_add_f32 v[152:153], v[152:153], 1.0 op_sel_hi:[1,0]
	v_pk_add_f32 v[154:155], v[154:155], 1.0 op_sel_hi:[1,0]
	v_pk_add_f32 v[156:157], v[156:157], 1.0 op_sel_hi:[1,0]
	v_pk_add_f32 v[158:159], v[158:159], 1.0 op_sel_hi:[1,0]
	v_rcp_f32_e32 v152, v152
	v_rcp_f32_e32 v153, v153
	v_rcp_f32_e32 v154, v154
	v_rcp_f32_e32 v155, v155
	v_rcp_f32_e32 v156, v156
	v_rcp_f32_e32 v157, v157
	v_rcp_f32_e32 v158, v158
	v_rcp_f32_e32 v159, v159
	v_pk_mul_f32 v[152:153], v[44:45], v[152:153]
	v_pk_mul_f32 v[154:155], v[46:47], v[154:155]
	v_pk_mul_f32 v[156:157], v[36:37], v[156:157]
	v_pk_mul_f32 v[158:159], v[38:39], v[158:159]
	v_pk_mul_f32 v[40:41], v[152:153], v[40:41]
	v_pk_mul_f32 v[42:43], v[154:155], v[42:43]
	v_pk_mul_f32 v[32:33], v[156:157], v[32:33]
	v_pk_mul_f32 v[34:35], v[158:159], v[34:35]
	v_cvt_pk_bf16_f32 v164, v40, v41
	v_cvt_pk_bf16_f32 v165, v42, v43
	v_cvt_pk_bf16_f32 v166, v32, v33
	v_cvt_pk_bf16_f32 v167, v34, v35
	global_store_dwordx4 v[146:147], v[164:167], off
	v_lshl_add_u64 v[146:147], v[146:147], 0, s[28:29]
	v_pk_mul_f32 v[152:153], v[28:29], v[150:151]
	v_pk_mul_f32 v[154:155], v[30:31], v[150:151]
	v_pk_mul_f32 v[156:157], v[20:21], v[150:151]
	v_pk_mul_f32 v[158:159], v[22:23], v[150:151]
	v_exp_f32_e32 v152, v152
	v_exp_f32_e32 v153, v153
	v_exp_f32_e32 v154, v154
	v_exp_f32_e32 v155, v155
	v_exp_f32_e32 v156, v156
	v_exp_f32_e32 v157, v157
	v_exp_f32_e32 v158, v158
	v_exp_f32_e32 v159, v159
	v_pk_add_f32 v[152:153], v[152:153], 1.0 op_sel_hi:[1,0]
	v_pk_add_f32 v[154:155], v[154:155], 1.0 op_sel_hi:[1,0]
	v_pk_add_f32 v[156:157], v[156:157], 1.0 op_sel_hi:[1,0]
	v_pk_add_f32 v[158:159], v[158:159], 1.0 op_sel_hi:[1,0]
	v_rcp_f32_e32 v152, v152
	v_rcp_f32_e32 v153, v153
	v_rcp_f32_e32 v154, v154
	v_rcp_f32_e32 v155, v155
	v_rcp_f32_e32 v156, v156
	v_rcp_f32_e32 v157, v157
	v_rcp_f32_e32 v158, v158
	v_rcp_f32_e32 v159, v159
	v_pk_mul_f32 v[152:153], v[28:29], v[152:153]
	v_pk_mul_f32 v[154:155], v[30:31], v[154:155]
	v_pk_mul_f32 v[156:157], v[20:21], v[156:157]
	v_pk_mul_f32 v[158:159], v[22:23], v[158:159]
	v_pk_mul_f32 v[24:25], v[152:153], v[24:25]
	v_pk_mul_f32 v[26:27], v[154:155], v[26:27]
	v_pk_mul_f32 v[16:17], v[156:157], v[16:17]
	v_pk_mul_f32 v[18:19], v[158:159], v[18:19]
	v_cvt_pk_bf16_f32 v160, v24, v25
	v_cvt_pk_bf16_f32 v161, v26, v27
	v_cvt_pk_bf16_f32 v162, v16, v17
	v_cvt_pk_bf16_f32 v163, v18, v19
	global_store_dwordx4 v[146:147], v[160:163], off
	v_lshl_add_u64 v[146:147], v[146:147], 0, s[28:29]
	v_pk_mul_f32 v[152:153], v[12:13], v[150:151]
	v_pk_mul_f32 v[154:155], v[14:15], v[150:151]
	v_pk_mul_f32 v[156:157], v[4:5], v[150:151]
	v_pk_mul_f32 v[158:159], v[6:7], v[150:151]
	v_exp_f32_e32 v152, v152
	v_exp_f32_e32 v153, v153
	v_exp_f32_e32 v154, v154
	v_exp_f32_e32 v155, v155
	v_exp_f32_e32 v156, v156
	v_exp_f32_e32 v157, v157
	v_exp_f32_e32 v158, v158
	v_exp_f32_e32 v159, v159
	v_pk_add_f32 v[152:153], v[152:153], 1.0 op_sel_hi:[1,0]
	v_pk_add_f32 v[154:155], v[154:155], 1.0 op_sel_hi:[1,0]
	v_pk_add_f32 v[156:157], v[156:157], 1.0 op_sel_hi:[1,0]
	v_pk_add_f32 v[158:159], v[158:159], 1.0 op_sel_hi:[1,0]
	v_rcp_f32_e32 v152, v152
	v_rcp_f32_e32 v153, v153
	v_rcp_f32_e32 v154, v154
	v_rcp_f32_e32 v155, v155
	v_rcp_f32_e32 v156, v156
	v_rcp_f32_e32 v157, v157
	v_rcp_f32_e32 v158, v158
	v_rcp_f32_e32 v159, v159
	v_pk_mul_f32 v[152:153], v[12:13], v[152:153]
	v_pk_mul_f32 v[154:155], v[14:15], v[154:155]
	v_pk_mul_f32 v[156:157], v[4:5], v[156:157]
	v_pk_mul_f32 v[158:159], v[6:7], v[158:159]
	v_pk_mul_f32 v[8:9], v[152:153], v[8:9]
	v_pk_mul_f32 v[10:11], v[154:155], v[10:11]
	v_pk_mul_f32 v[0:1], v[156:157], v[0:1]
	v_pk_mul_f32 v[2:3], v[158:159], v[2:3]
	v_cvt_pk_bf16_f32 v164, v8, v9
	v_cvt_pk_bf16_f32 v165, v10, v11
	v_cvt_pk_bf16_f32 v166, v0, v1
	v_cvt_pk_bf16_f32 v167, v2, v3
	global_store_dwordx4 v[146:147], v[164:167], off
	s_mov_b64 s[28:29], -1
	s_cbranch_vccnz .LBB0_1396
	s_andn2_b64 vcc, exec, s[30:31]
	s_cbranch_vccnz .LBB0_1395
	s_barrier
	s_branch .LBB0_1395
